# v098 with the single P10 per-token barrier moved behind the issue of the epilogue loads (none at the token top)
# speedup vs baseline: 1.0067x; 1.0067x over previous
; __global__ void __launch_bounds__(NT, 2) mk_fwd(Args args) {
;     ...
;             float* xr = args.out + (size_t)tok * DM + lane * 32; const float* gt2 = MOD + (size_t)b * NMODC + 5 * DM + lane * 32;
;             float ss = 0.f;
; #pragma unroll
;             for (int q = 0; q < 8; ++q) { const f32x4 xv = *(const f32x4*)(xr + q * 4), g4 = *(const f32x4*)(gt2 + q * 4);
.LBB0_885:
	s_ashr_i32 s10, s70, 11
	s_lshl_b64 s[4:5], s[70:71], 13
	v_lshl_add_u64 v[0:1], v[102:103], 0, s[4:5]
	s_mul_hi_i32 s5, s10, 0xc000
	s_mul_i32 s10, s10, 0xc000
	s_add_u32 s4, s74, s10
	s_addc_u32 s5, s75, s5
	v_lshl_add_u64 v[54:55], s[4:5], 0, v[136:137]
	v_lshl_add_u64 v[66:67], v[54:55], 0, s[8:9]
	global_load_dwordx4 v[2:5], v[0:1], off offset:48
	global_load_dwordx4 v[6:9], v[0:1], off offset:32
	global_load_dwordx4 v[10:13], v[0:1], off offset:16
	global_load_dwordx4 v[14:17], v[0:1], off
	global_load_dwordx4 v[18:21], v[66:67], off offset:32
	global_load_dwordx4 v[22:25], v[66:67], off offset:16
	global_load_dwordx4 v[26:29], v[66:67], off offset:48
	global_load_dwordx4 v[30:33], v[0:1], off offset:96
	global_load_dwordx4 v[34:37], v[0:1], off offset:80
	global_load_dwordx4 v[38:41], v[0:1], off offset:64
	global_load_dwordx4 v[42:45], v[66:67], off offset:64
	global_load_dwordx4 v[46:49], v[66:67], off offset:96
	global_load_dwordx4 v[50:53], v[66:67], off offset:80
	v_add_co_u32_e32 v68, vcc, s28, v54
	s_add_i32 s70, s70, s72
	s_nop 0
	v_addc_co_u32_e32 v69, vcc, 0, v55, vcc
	global_load_dwordx4 v[54:57], v[68:69], off
	global_load_dwordx4 v[58:61], v[0:1], off offset:112
	global_load_dwordx4 v[62:65], v[66:67], off offset:112
	s_cmp_eq_u32 s84, 0x100
	s_cbranch_scc0 .Lp10_nobar
	s_barrier
; __device__ __forceinline__ float wave_sum(float v) { v = row16_sum(v); v += __shfl_xor(v, 16); v += __shfl_xor(v, 32); return v; }
; __global__ void __launch_bounds__(NT, 2) mk_fwd(Args args) {
;     ...
;             float* xr = args.out + (size_t)tok * DM + lane * 32; const float* gt2 = MOD + (size_t)b * NMODC + 5 * DM + lane * 32;
;             float ss = 0.f;
; #pragma unroll
;             for (int q = 0; q < 8; ++q) { const f32x4 xv = *(const f32x4*)(xr + q * 4), g4 = *(const f32x4*)(gt2 + q * 4);
;                 float* a = acc + q * 4;
;                 a[0] = xv.x + g4.x * a[0]; a[1] = xv.y + g4.y * a[1]; a[2] = xv.z + g4.z * a[2]; a[3] = xv.w + g4.w * a[3];
;                 ss += (a[0] * a[0] + a[1] * a[1]) + (a[2] * a[2] + a[3] * a[3]); }
;             ss = wave_sum(ss);
;             const float rinv = rsqrtf(ss * (1.0f / DM) + 1e-6f);
; #pragma unroll
;             for (int q = 0; q < 8; ++q) { const f32x4 f4 = *(const f32x4*)(fg + lane * 32 + q * 4); const float* a = acc + q * 4;
;                 *(f32x4*)(xr + q * 4) = (f32x4){a[0] * rinv * f4.x, a[1] * rinv * f4.y, a[2] * rinv * f4.z, a[3] * rinv * f4.w}; }
.Lp10_nobar:
	s_cmpk_gt_i32 s70, 0x3fff
	s_waitcnt vmcnt(11)
	v_pk_fma_f32 v[6:7], v[18:19], v[140:141], v[6:7]
	s_waitcnt vmcnt(10)
	v_pk_fma_f32 v[10:11], v[22:23], v[144:145], v[10:11]
	v_pk_fma_f32 v[12:13], v[24:25], v[142:143], v[12:13]
	v_pk_fma_f32 v[8:9], v[20:21], v[138:139], v[8:9]
	s_waitcnt vmcnt(9)
	v_pk_fma_f32 v[18:19], v[26:27], v[134:135], v[2:3]
	v_pk_fma_f32 v[20:21], v[28:29], v[132:133], v[4:5]
	s_waitcnt vmcnt(2)
	v_pk_fma_f32 v[2:3], v[54:55], v[118:119], v[14:15]
	v_pk_fma_f32 v[4:5], v[56:57], v[122:123], v[16:17]
	v_pk_fma_f32 v[28:29], v[52:53], v[120:121], v[36:37]
	v_mov_b32_e32 v17, v11
	v_mov_b32_e32 v37, v13
	v_mov_b32_e32 v16, v3
	v_mov_b32_e32 v36, v5
	v_pk_fma_f32 v[24:25], v[44:45], v[126:127], v[40:41]
	v_pk_fma_f32 v[26:27], v[50:51], v[124:125], v[34:35]
	v_mov_b32_e32 v15, v10
	v_mov_b32_e32 v35, v12
	v_mov_b32_e32 v40, v7
	v_mov_b32_e32 v41, v9
	v_mov_b32_e32 v14, v2
	v_mov_b32_e32 v34, v4
	v_pk_mul_f32 v[16:17], v[16:17], v[16:17]
	v_pk_mul_f32 v[36:37], v[36:37], v[36:37]
	v_pk_fma_f32 v[22:23], v[42:43], v[130:131], v[38:39]
	v_mov_b32_e32 v38, v6
	v_mov_b32_e32 v39, v8
	v_pk_mul_f32 v[40:41], v[40:41], v[40:41]
	v_pk_fma_f32 v[14:15], v[14:15], v[14:15], v[16:17]
	v_pk_fma_f32 v[16:17], v[34:35], v[34:35], v[36:37]
	v_mul_f32_e32 v42, v19, v19
	v_mul_f32_e32 v44, v21, v21
	v_pk_fma_f32 v[38:39], v[38:39], v[38:39], v[40:41]
	v_pk_add_f32 v[14:15], v[14:15], v[16:17]
	v_pk_fma_f32 v[30:31], v[46:47], v[116:117], v[30:31]
	v_pk_fma_f32 v[32:33], v[48:49], v[114:115], v[32:33]
	v_pk_mul_f32 v[46:47], v[22:23], v[22:23]
	v_pk_mul_f32 v[48:49], v[24:25], v[24:25]
	v_pk_fma_f32 v[42:43], v[18:19], v[18:19], v[42:43] op_sel_hi:[1,1,0]
	v_pk_fma_f32 v[44:45], v[20:21], v[20:21], v[44:45] op_sel_hi:[1,1,0]
	v_pk_add_f32 v[34:35], v[38:39], v[38:39] op_sel:[0,1] op_sel_hi:[1,0]
	v_pk_add_f32 v[14:15], v[14:15], v[14:15] op_sel:[0,1] op_sel_hi:[1,0]
	v_mov_b32_e32 v52, v27
	v_mov_b32_e32 v53, v29
	v_mov_b32_e32 v43, v48
	v_mov_b32_e32 v45, v49
	v_mov_b32_e32 v35, v47
	v_mov_b32_e32 v15, v46
	v_mov_b32_e32 v50, v26
	v_mov_b32_e32 v51, v28
	v_pk_mul_f32 v[52:53], v[52:53], v[52:53]
	v_pk_add_f32 v[36:37], v[42:43], v[44:45]
	v_pk_add_f32 v[14:15], v[14:15], v[34:35]
	v_mul_f32_e32 v54, v31, v31
	v_mul_f32_e32 v56, v33, v33
	s_waitcnt vmcnt(0)
	v_pk_fma_f32 v[58:59], v[62:63], v[112:113], v[58:59]
	v_pk_fma_f32 v[60:61], v[64:65], v[110:111], v[60:61]
	v_pk_fma_f32 v[40:41], v[50:51], v[50:51], v[52:53]
	v_pk_add_f32 v[14:15], v[14:15], v[36:37]
	v_pk_fma_f32 v[54:55], v[30:31], v[30:31], v[54:55] op_sel_hi:[1,1,0]
	v_pk_fma_f32 v[56:57], v[32:33], v[32:33], v[56:57] op_sel_hi:[1,1,0]
	v_pk_mul_f32 v[62:63], v[58:59], v[58:59]
	v_pk_mul_f32 v[64:65], v[60:61], v[60:61]
	v_pk_add_f32 v[38:39], v[40:41], v[40:41] op_sel:[0,1] op_sel_hi:[1,0]
	v_pk_add_f32 v[14:15], v[14:15], v[14:15] op_sel:[0,1] op_sel_hi:[1,0]
	v_mov_b32_e32 v55, v64
	v_mov_b32_e32 v39, v63
	v_mov_b32_e32 v15, v62
	v_mov_b32_e32 v57, v65
	v_pk_add_f32 v[14:15], v[14:15], v[38:39]
	v_pk_add_f32 v[16:17], v[54:55], v[56:57]
	s_nop 0
	v_pk_add_f32 v[14:15], v[14:15], v[16:17]
	s_nop 0
	v_add_f32_e32 v14, v14, v15
	s_nop 1
	v_add_f32_dpp v14, v14, v14 quad_perm:[1,0,3,2] row_mask:0xf bank_mask:0xf bound_ctrl:1
	s_nop 1
	v_add_f32_dpp v14, v14, v14 quad_perm:[2,3,0,1] row_mask:0xf bank_mask:0xf bound_ctrl:1
	s_nop 1
	v_add_f32_dpp v14, v14, v14 row_half_mirror row_mask:0xf bank_mask:0xf bound_ctrl:1
	s_nop 1
	v_add_f32_dpp v14, v14, v14 row_mirror row_mask:0xf bank_mask:0xf bound_ctrl:1
	ds_bpermute_b32 v15, v146, v14
	s_waitcnt lgkmcnt(0)
	v_add_f32_e32 v14, v14, v15
	ds_bpermute_b32 v15, v129, v14
	s_waitcnt lgkmcnt(0)
	v_add_f32_e32 v14, v14, v15
	v_fmamk_f32 v14, v14, 0x3a000000, v153
	v_mul_f32_e32 v15, 0x4b800000, v14
	v_cmp_gt_f32_e32 vcc, s29, v14
	s_nop 1
	v_cndmask_b32_e32 v14, v14, v15, vcc
	v_rsq_f32_e32 v14, v14
	s_nop 0
	v_mul_f32_e32 v15, 0x45800000, v14
	v_cndmask_b32_e32 v14, v14, v15, vcc
	v_pk_mul_f32 v[2:3], v[14:15], v[2:3] op_sel_hi:[0,1]
	v_pk_mul_f32 v[4:5], v[14:15], v[4:5] op_sel_hi:[0,1]
	v_pk_mul_f32 v[10:11], v[14:15], v[10:11] op_sel_hi:[0,1]
	v_pk_mul_f32 v[12:13], v[14:15], v[12:13] op_sel_hi:[0,1]
	v_pk_mul_f32 v[6:7], v[14:15], v[6:7] op_sel_hi:[0,1]
	v_pk_mul_f32 v[8:9], v[14:15], v[8:9] op_sel_hi:[0,1]
	v_pk_mul_f32 v[18:19], v[14:15], v[18:19] op_sel_hi:[0,1]
	v_pk_mul_f32 v[20:21], v[14:15], v[20:21] op_sel_hi:[0,1]
	v_pk_mul_f32 v[22:23], v[14:15], v[22:23] op_sel_hi:[0,1]
	v_pk_mul_f32 v[24:25], v[14:15], v[24:25] op_sel_hi:[0,1]
	v_pk_mul_f32 v[26:27], v[14:15], v[26:27] op_sel_hi:[0,1]
	v_pk_mul_f32 v[28:29], v[14:15], v[28:29] op_sel_hi:[0,1]
	v_pk_mul_f32 v[30:31], v[14:15], v[30:31] op_sel_hi:[0,1]
	v_pk_mul_f32 v[32:33], v[14:15], v[32:33] op_sel_hi:[0,1]
	v_pk_mul_f32 v[58:59], v[14:15], v[58:59] op_sel_hi:[0,1]
	v_pk_mul_f32 v[60:61], v[14:15], v[60:61] op_sel_hi:[0,1]
	v_pk_mul_f32 v[2:3], v[186:187], v[2:3]
	v_pk_mul_f32 v[4:5], v[188:189], v[4:5]
	global_store_dwordx4 v[0:1], v[2:5], off
	v_pk_mul_f32 v[10:11], v[190:191], v[10:11]
	v_pk_mul_f32 v[12:13], v[192:193], v[12:13]
	global_store_dwordx4 v[0:1], v[10:13], off offset:16
	v_pk_mul_f32 v[6:7], v[194:195], v[6:7]
	v_pk_mul_f32 v[8:9], v[196:197], v[8:9]
	global_store_dwordx4 v[0:1], v[6:9], off offset:32
	v_pk_mul_f32 v[18:19], v[198:199], v[18:19]
	v_pk_mul_f32 v[20:21], v[200:201], v[20:21]
	global_store_dwordx4 v[0:1], v[18:21], off offset:48
	v_pk_mul_f32 v[22:23], v[202:203], v[22:23]
	v_pk_mul_f32 v[24:25], v[204:205], v[24:25]
	global_store_dwordx4 v[0:1], v[22:25], off offset:64
	v_pk_mul_f32 v[26:27], v[206:207], v[26:27]
	v_pk_mul_f32 v[28:29], v[208:209], v[28:29]
	global_store_dwordx4 v[0:1], v[26:29], off offset:80
	v_pk_mul_f32 v[30:31], v[210:211], v[30:31]
	v_pk_mul_f32 v[32:33], v[212:213], v[32:33]
	global_store_dwordx4 v[0:1], v[30:33], off offset:96
	v_pk_mul_f32 v[58:59], v[214:215], v[58:59]
	v_pk_mul_f32 v[60:61], v[216:217], v[60:61]
	global_store_dwordx4 v[0:1], v[58:61], off offset:112
	s_cbranch_scc1 .LBB0_913
